# merge register parking: in layer 1 only the two constants still needed afterwards are saved/reloaded
# baseline (speedup 1.0000x reference)
.LBB0_661:
	s_or_b64 exec, exec, s[0:1]
	v_readlane_b32 s2, v253, 46
	v_readlane_b32 s3, v253, 47
	s_mov_b64 s[0:1], 0
	v_mov_b32_e32 v14, v197
	s_waitcnt lgkmcnt(0)
	v_cndmask_b32_e64 v0, 0, 1, s[2:3]
	s_barrier
	s_barrier
	v_cmp_ne_u32_e64 s[4:5], 1, v0
	s_andn2_b64 vcc, exec, s[2:3]
	v_readfirstlane_b32 s2, v14
	s_cbranch_vccnz .LBB0_707
	s_lshl_b32 s87, s52, 11
	v_lshl_add_u32 v243, v197, 2, s87
	s_add_u32 s88, s96, 0x6100000
	s_addc_u32 s89, s97, 0
	global_store_dword v243, v220, s[88:89]
	s_add_u32 s88, s88, 0x80000
	s_addc_u32 s89, s89, 0
	global_store_dword v243, v235, s[88:89]
	s_add_u32 s88, s88, 0x80000
	s_addc_u32 s89, s89, 0
	v_readlane_b32 s87, v252, 23
	s_nop 3
	s_cmp_eq_u32 s87, 0
	s_cbranch_scc1 .Lmrs_st_end
	global_store_dword v243, v196, s[88:89]
	s_add_u32 s88, s88, 0x80000
	s_addc_u32 s89, s89, 0
	global_store_dword v243, v198, s[88:89]
	s_add_u32 s88, s88, 0x80000
	s_addc_u32 s89, s89, 0
	global_store_dword v243, v199, s[88:89]
	s_add_u32 s88, s88, 0x80000
	s_addc_u32 s89, s89, 0
	global_store_dword v243, v200, s[88:89]
	s_add_u32 s88, s88, 0x80000
	s_addc_u32 s89, s89, 0
	global_store_dword v243, v201, s[88:89]
	s_add_u32 s88, s88, 0x80000
	s_addc_u32 s89, s89, 0
	global_store_dword v243, v218, s[88:89]
	s_add_u32 s88, s88, 0x80000
	s_addc_u32 s89, s89, 0
	global_store_dword v243, v219, s[88:89]
	s_add_u32 s88, s88, 0x80000
	s_addc_u32 s89, s89, 0
	global_store_dword v243, v222, s[88:89]
	s_add_u32 s88, s88, 0x80000
	s_addc_u32 s89, s89, 0
	global_store_dword v243, v223, s[88:89]
	s_add_u32 s88, s88, 0x80000
	s_addc_u32 s89, s89, 0
	global_store_dword v243, v224, s[88:89]
	s_add_u32 s88, s88, 0x80000
	s_addc_u32 s89, s89, 0
	global_store_dword v243, v225, s[88:89]
	s_add_u32 s88, s88, 0x80000
	s_addc_u32 s89, s89, 0
	global_store_dword v243, v226, s[88:89]
	s_add_u32 s88, s88, 0x80000
	s_addc_u32 s89, s89, 0
	global_store_dword v243, v227, s[88:89]
	s_add_u32 s88, s88, 0x80000
	s_addc_u32 s89, s89, 0
	global_store_dword v243, v228, s[88:89]
	s_add_u32 s88, s88, 0x80000
	s_addc_u32 s89, s89, 0
	global_store_dword v243, v229, s[88:89]
	s_add_u32 s88, s88, 0x80000
	s_addc_u32 s89, s89, 0
	global_store_dword v243, v230, s[88:89]
	s_add_u32 s88, s88, 0x80000
	s_addc_u32 s89, s89, 0
	global_store_dword v243, v231, s[88:89]
	s_add_u32 s88, s88, 0x80000
	s_addc_u32 s89, s89, 0
	global_store_dword v243, v232, s[88:89]
	s_add_u32 s88, s88, 0x80000
	s_addc_u32 s89, s89, 0
	global_store_dword v243, v233, s[88:89]
	s_add_u32 s88, s88, 0x80000
	s_addc_u32 s89, s89, 0
	global_store_dword v243, v234, s[88:89]
	s_add_u32 s88, s88, 0x80000
	s_addc_u32 s89, s89, 0
.Lmrs_st_end:
	v_lshlrev_b32_e32 v0, 4, v14
	v_add_u32_e32 v1, 0x2000, v0
	v_ashrrev_i32_e32 v2, 31, v1
	v_lshrrev_b32_e32 v2, 22, v2
	v_add_u32_e32 v2, v1, v2
	v_ashrrev_i32_e32 v8, 10, v2
	v_mul_i32_i24_e32 v3, 0x400, v8
	v_sub_u32_e32 v1, v1, v3
	v_lshrrev_b32_e32 v3, 4, v1
	v_bitop3_b32 v1, v3, v1, 32 bitop3:0x6c
	v_ashrrev_i32_e32 v3, 31, v1
	v_lshrrev_b32_e32 v3, 26, v3
	v_add_u32_e32 v3, v1, v3
	v_ashrrev_i32_e32 v9, 6, v3
	v_and_b32_e32 v3, 0xc0, v3
	v_sub_u32_e32 v1, v1, v3
	v_lshlrev_b32_e32 v2, 5, v8
	v_ashrrev_i16_sdwa v1, v221, sext(v1) dst_sel:DWORD dst_unused:UNUSED_PAD src0_sel:DWORD src1_sel:BYTE_0
	v_and_b32_e32 v2, 32, v2
	v_bfe_i32 v10, v1, 0, 16
	v_add_u32_e32 v1, v2, v10
	v_lshlrev_b32_e32 v2, 3, v8
	v_and_b32_e32 v2, 0x1ffff0, v2
	v_add_lshl_u32 v2, v9, v2, 11
	v_lshl_add_u32 v204, v1, 1, v2
	v_bfe_i32 v2, v14, 27, 1
	v_lshrrev_b32_e32 v2, 22, v2
	v_add_u32_e32 v2, v0, v2
	v_and_b32_e32 v2, 0xfffffc00, v2
	s_add_u32 s3, s96, s0
	v_sub_u32_e32 v0, v0, v2
	s_addc_u32 s18, s97, s1
	v_lshrrev_b32_e32 v2, 4, v0
	s_add_u32 s19, s3, 0xd000000
	v_bitop3_b32 v2, v2, v0, 32 bitop3:0x6c
	v_ashrrev_i32_e32 v0, 31, v0
	s_addc_u32 s20, s18, 0
	s_lshl_b32 s0, s50, 21
	v_lshrrev_b32_e32 v0, 26, v0
	s_add_u32 s0, s3, s0
	v_ashrrev_i32_e32 v1, 31, v14
	v_add_u32_e32 v0, v2, v0
	s_addc_u32 s1, s18, 0
	v_lshrrev_b32_e32 v1, 26, v1
	v_ashrrev_i32_e32 v12, 6, v0
	s_add_u32 s21, s0, 0x10100000
	v_add_u32_e32 v1, v14, v1
	v_mul_i32_i24_e32 v0, 64, v12
	s_addc_u32 s22, s1, 0
	s_ashr_i32 s6, s2, 6
	v_ashrrev_i32_e32 v11, 6, v1
	v_sub_u32_e32 v0, v2, v0
	s_ashr_i32 s7, s2, 8
	s_lshl_b32 s23, s6, 10
	v_lshlrev_b32_e32 v1, 5, v11
	v_ashrrev_i16_sdwa v0, v221, sext(v0) dst_sel:DWORD dst_unused:UNUSED_PAD src0_sel:DWORD src1_sel:BYTE_0
	s_add_u32 s8, s19, s65
	v_and_b32_e32 v1, 32, v1
	v_bfe_i32 v13, v0, 0, 16
	s_addc_u32 s9, s20, 0
	v_add_u32_e32 v0, v1, v13
	v_lshlrev_b32_e32 v1, 3, v11
	s_add_u32 s14, s21, s66
	v_and_b32_e32 v1, 0x1ffff0, v1
	s_addc_u32 s15, s22, 0
	v_add_lshl_u32 v1, v12, v1, 11
	s_add_i32 s24, s23, 0
	v_lshl_add_u32 v194, v0, 1, v1
	s_add_i32 m0, s24, 0x10000
	s_add_i32 s25, s24, 0x2000
	global_load_lds_dwordx4 v194, s[14:15]
	s_add_i32 m0, s24, 0x12000
	s_add_u32 s0, s14, 0x40000
	global_load_lds_dwordx4 v204, s[14:15]
	s_mov_b32 m0, s24
	s_addc_u32 s1, s15, 0
	global_load_lds_dwordx4 v194, s[8:9]
	s_mov_b32 m0, s25
	v_mov_b32_e32 v205, v195
	global_load_lds_dwordx4 v204, s[8:9]
	s_add_i32 m0, s24, 0x14000
	v_lshl_add_u64 v[6:7], s[14:15], 0, v[194:195]
	global_load_lds_dwordx4 v194, s[0:1]
	s_add_i32 m0, s24, 0x16000
	v_lshl_add_u64 v[4:5], s[14:15], 0, v[204:205]
	global_load_lds_dwordx4 v204, s[0:1]
	s_add_u32 s0, s8, 0x40000
	s_addc_u32 s1, s9, 0
	s_add_i32 s26, s24, 0x4000
	s_mov_b32 m0, s26
	s_add_i32 s27, s24, 0x6000
	global_load_lds_dwordx4 v194, s[0:1]
	s_mov_b32 m0, s27
	v_lshl_add_u64 v[2:3], s[8:9], 0, v[194:195]
	global_load_lds_dwordx4 v204, s[0:1]
	s_cmp_lg_u32 s7, 1
	v_lshl_add_u64 v[0:1], s[8:9], 0, v[204:205]
	s_cbranch_scc1 .LBB0_664
	s_barrier

.LBB0_706:
	s_movk_i32 s41, 0x70
	s_barrier
	s_lshl_b32 s87, s52, 11
	v_lshl_add_u32 v243, v197, 2, s87
	s_add_u32 s88, s96, 0x6100000
	s_addc_u32 s89, s97, 0
	global_load_dword v220, v243, s[88:89]
	s_add_u32 s88, s88, 0x80000
	s_addc_u32 s89, s89, 0
	global_load_dword v235, v243, s[88:89]
	s_add_u32 s88, s88, 0x80000
	s_addc_u32 s89, s89, 0
	v_readlane_b32 s87, v252, 23
	s_nop 3
	s_cmp_eq_u32 s87, 0
	s_cbranch_scc1 .Lmrs_ld_end
	global_load_dword v196, v243, s[88:89]
	s_add_u32 s88, s88, 0x80000
	s_addc_u32 s89, s89, 0
	global_load_dword v198, v243, s[88:89]
	s_add_u32 s88, s88, 0x80000
	s_addc_u32 s89, s89, 0
	global_load_dword v199, v243, s[88:89]
	s_add_u32 s88, s88, 0x80000
	s_addc_u32 s89, s89, 0
	global_load_dword v200, v243, s[88:89]
	s_add_u32 s88, s88, 0x80000
	s_addc_u32 s89, s89, 0
	global_load_dword v201, v243, s[88:89]
	s_add_u32 s88, s88, 0x80000
	s_addc_u32 s89, s89, 0
	global_load_dword v218, v243, s[88:89]
	s_add_u32 s88, s88, 0x80000
	s_addc_u32 s89, s89, 0
	global_load_dword v219, v243, s[88:89]
	s_add_u32 s88, s88, 0x80000
	s_addc_u32 s89, s89, 0
	global_load_dword v222, v243, s[88:89]
	s_add_u32 s88, s88, 0x80000
	s_addc_u32 s89, s89, 0
	global_load_dword v223, v243, s[88:89]
	s_add_u32 s88, s88, 0x80000
	s_addc_u32 s89, s89, 0
	global_load_dword v224, v243, s[88:89]
	s_add_u32 s88, s88, 0x80000
	s_addc_u32 s89, s89, 0
	global_load_dword v225, v243, s[88:89]
	s_add_u32 s88, s88, 0x80000
	s_addc_u32 s89, s89, 0
	global_load_dword v226, v243, s[88:89]
	s_add_u32 s88, s88, 0x80000
	s_addc_u32 s89, s89, 0
	global_load_dword v227, v243, s[88:89]
	s_add_u32 s88, s88, 0x80000
	s_addc_u32 s89, s89, 0
	global_load_dword v228, v243, s[88:89]
	s_add_u32 s88, s88, 0x80000
	s_addc_u32 s89, s89, 0
	global_load_dword v229, v243, s[88:89]
	s_add_u32 s88, s88, 0x80000
	s_addc_u32 s89, s89, 0
	global_load_dword v230, v243, s[88:89]
	s_add_u32 s88, s88, 0x80000
	s_addc_u32 s89, s89, 0
	global_load_dword v231, v243, s[88:89]
	s_add_u32 s88, s88, 0x80000
	s_addc_u32 s89, s89, 0
	global_load_dword v232, v243, s[88:89]
	s_add_u32 s88, s88, 0x80000
	s_addc_u32 s89, s89, 0
	global_load_dword v233, v243, s[88:89]
	s_add_u32 s88, s88, 0x80000
	s_addc_u32 s89, s89, 0
	global_load_dword v234, v243, s[88:89]
	s_add_u32 s88, s88, 0x80000
	s_addc_u32 s89, s89, 0
.Lmrs_ld_end:
.LBB0_707:
	s_waitcnt vmcnt(0)
	s_waitcnt lgkmcnt(0)
	s_barrier
	s_and_saveexec_b64 s[0:1], s[54:55]
	s_cbranch_execz .LBB0_759
	s_mov_b32 s2, s53
	s_mov_b64 s[6:7], 0
	v_mov_b32_e32 v0, s73
	s_waitcnt vmcnt(0) expcnt(0) lgkmcnt(0)
	ds_read_b32 v2, v0
	v_mov_b32_e32 v0, s74
	ds_read_b32 v0, v0
	s_lshl_b64 s[6:7], s[6:7], 2
	v_readlane_b32 s8, v253, 24
	v_readlane_b32 s9, v253, 25
	s_add_u32 s6, s8, s6
	s_waitcnt lgkmcnt(1)
	v_cmp_ne_u32_e32 vcc, 0, v2
	s_addc_u32 s7, s9, s7
	s_cbranch_vccnz .LBB0_723
	s_add_u32 s8, s6, 0x1000
	s_addc_u32 s9, s7, 0
	s_add_u32 s10, s6, 0x1100
	s_addc_u32 s11, s7, 0
	s_add_u32 s12, s6, 0x1200
	s_addc_u32 s13, s7, 0
	s_add_u32 s14, s6, 0x1300
	s_addc_u32 s15, s7, 0
	s_mov_b32 s3, 1
	s_branch .LBB0_711
